# pool items: gate vectors and all pool_scale vectors requested before the window-sum loop instead of inside the MFMA block
# baseline (speedup 1.0000x reference)
.LBB0_1245:
	s_or_b64 exec, exec, s[10:11]
	s_movk_i32 s2, 0x1000
	v_add_co_u32_e32 v2, vcc, s2, v0
	s_movk_i32 s2, 0x3000
	s_nop 0
	v_addc_co_u32_e32 v3, vcc, 0, v1, vcc
	v_add_co_u32_e32 v126, vcc, s1, v0
	global_load_dwordx4 v[122:125], v[0:1], off
	global_load_dwordx4 v[118:121], v[0:1], off offset:64
	global_load_dwordx4 v[114:117], v[0:1], off offset:128
	global_load_dwordx4 v[110:113], v[0:1], off offset:192
	v_addc_co_u32_e32 v127, vcc, 0, v1, vcc
	v_add_co_u32_e32 v4, vcc, s2, v0
	s_movk_i32 s2, 0x4000
	s_nop 0
	v_addc_co_u32_e32 v5, vcc, 0, v1, vcc
	v_add_co_u32_e32 v6, vcc, s2, v0
	s_movk_i32 s2, 0x5000
	s_nop 0
	v_addc_co_u32_e32 v7, vcc, 0, v1, vcc
	global_load_dwordx4 v[106:109], v[2:3], off offset:64
	global_load_dwordx4 v[102:105], v[2:3], off offset:128
	global_load_dwordx4 v[98:101], v[126:127], off
	global_load_dwordx4 v[94:97], v[126:127], off offset:64
	global_load_dwordx4 v[90:93], v[126:127], off offset:128
	global_load_dwordx4 v[24:27], v[126:127], off offset:192
	global_load_dwordx4 v[28:31], v[2:3], off offset:192
	global_load_dwordx4 v[82:85], v[4:5], off offset:64
	global_load_dwordx4 v[78:81], v[4:5], off offset:128
	global_load_dwordx4 v[16:19], v[4:5], off offset:192
	global_load_dwordx4 v[86:89], v[6:7], off offset:-4096
	global_load_dwordx4 v[74:77], v[6:7], off
	global_load_dwordx4 v[70:73], v[6:7], off offset:64
	global_load_dwordx4 v[66:69], v[6:7], off offset:128
	v_add_co_u32_e32 v2, vcc, s2, v0
	s_movk_i32 s2, 0x6000
	s_nop 0
	v_addc_co_u32_e32 v3, vcc, 0, v1, vcc
	v_add_co_u32_e32 v4, vcc, s2, v0
	v_readlane_b32 s8, v253, 23
	s_nop 0
	v_addc_co_u32_e32 v5, vcc, 0, v1, vcc
	global_load_dwordx4 v[20:23], v[6:7], off offset:192
	global_load_dwordx4 v[62:65], v[4:5], off offset:-4096
	global_load_dwordx4 v[58:61], v[2:3], off offset:64
	global_load_dwordx4 v[54:57], v[2:3], off offset:128
	global_load_dwordx4 v[50:53], v[4:5], off
	global_load_dwordx4 v[46:49], v[4:5], off offset:64
	global_load_dwordx4 v[42:45], v[4:5], off offset:128
	global_load_dwordx4 v[8:11], v[4:5], off offset:192
	v_add_co_u32_e32 v0, vcc, 0x7000, v0
	v_lshlrev_b32_e32 v130, 4, v165
	s_nop 0
	v_addc_co_u32_e32 v1, vcc, 0, v1, vcc
	global_load_dwordx4 v[12:15], v[2:3], off offset:192
	global_load_dwordx4 v[38:41], v[0:1], off
	global_load_dwordx4 v[34:37], v[0:1], off offset:64
	global_load_dwordx4 v[4:7], v[0:1], off offset:128
	s_nop 0
	global_load_dwordx4 v[126:129], v[126:127], off offset:-4096
	s_nop 0
	global_load_dwordx4 v[0:3], v[0:1], off offset:192
	v_mov_b32_e32 v131, v33
	v_readlane_b32 s9, v253, 24
	s_movk_i32 s2, 0x8f0
	v_readfirstlane_b32 s17, v164
	v_lshl_add_u64 v[136:137], s[8:9], 0, v[130:131]
	v_add_u32_e32 v134, 0, v130
	s_waitcnt vmcnt(32)
	s_movk_i32 s8, 0x8f0
	v_cmp_gt_i32_e32 vcc, s8, v164
	s_and_saveexec_b64 s[10:11], vcc
	ds_write_b128 v204, v[232:235]
	s_or_b64 exec, exec, s[10:11]
	s_movk_i32 s8, 0x6f0
	v_cmp_gt_i32_e32 vcc, s8, v164
	s_and_saveexec_b64 s[10:11], vcc
	ds_write_b128 v205, v[188:191]
	s_or_b64 exec, exec, s[10:11]
	s_movk_i32 s8, 0x4f0
	v_cmp_gt_i32_e32 vcc, s8, v164
	s_and_saveexec_b64 s[10:11], vcc
	ds_write_b128 v206, v[192:195]
	s_or_b64 exec, exec, s[10:11]
	s_movk_i32 s8, 0x2f0
	v_cmp_gt_i32_e32 vcc, s8, v164
	s_and_saveexec_b64 s[10:11], vcc
	ds_write_b128 v207, v[196:199]
	s_or_b64 exec, exec, s[10:11]
	s_movk_i32 s8, 0xf0
	v_cmp_gt_i32_e32 vcc, s8, v164
	s_and_saveexec_b64 s[10:11], vcc
	ds_write_b128 v208, v[200:203]
	s_or_b64 exec, exec, s[10:11]
	v_ashrrev_i32_e32 v168, 2, v164
	v_lshlrev_b32_e32 v130, 6, v164
	v_mul_lo_u32 v166, v168, s33
	v_and_b32_e32 v167, 0xc0, v130
	v_readlane_b32 s2, v254, 56
	v_mov_b32_e32 v130, 0
	v_mov_b32_e32 v131, v130
	v_add3_u32 v169, v166, v167, s2
	v_readlane_b32 s2, v253, 19
	v_mov_b32_e32 v160, v130
	v_mov_b32_e32 v161, v130
	v_mov_b32_e32 v158, v130
	v_mov_b32_e32 v159, v130
	v_mov_b32_e32 v156, v130
	v_mov_b32_e32 v157, v130
	v_mov_b32_e32 v154, v130
	v_mov_b32_e32 v155, v130
	v_mov_b32_e32 v152, v130
	v_mov_b32_e32 v153, v130
	v_mov_b32_e32 v150, v130
	v_mov_b32_e32 v151, v130
	v_mov_b32_e32 v148, v130
	v_mov_b32_e32 v149, v130
	v_mov_b32_e32 v146, v130
	v_mov_b32_e32 v147, v130
	v_mov_b32_e32 v144, v130
	v_mov_b32_e32 v145, v130
	v_mov_b32_e32 v142, v130
	v_mov_b32_e32 v143, v130
	v_mov_b32_e32 v140, v130
	v_mov_b32_e32 v141, v130
	v_mov_b32_e32 v138, v130
	v_mov_b32_e32 v139, v130
	v_mov_b32_e32 v136, v130
	v_mov_b32_e32 v137, v130
	v_mov_b32_e32 v134, v130
	v_mov_b32_e32 v135, v130
	v_mov_b32_e32 v132, v130
	v_mov_b32_e32 v133, v130
	s_waitcnt lgkmcnt(0)
	s_ashr_i32 s9, s17, 2
	v_and_or_b32 v227, s9, -16, v165
	v_readlane_b32 s9, v253, 30
	v_mov_b64_e32 v[244:245], s[24:25]
	v_lshlrev_b32_e32 v222, 3, v163
	s_nop 1
	v_add_u32_e32 v227, s9, v227
	v_add_co_u32_e32 v244, vcc, v244, v222
	v_readlane_b32 s9, v253, 21
	s_nop 1
	v_addc_co_u32_e32 v245, vcc, 0, v245, vcc
	s_nop 1
	v_mad_i64_i32 v[244:245], s[14:15], v227, s70, v[244:245]
	s_lshl_b32 s10, s9, 1
	s_add_u32 s10, s10, 0x11101000
	s_mov_b32 s11, 0
	v_lshl_add_u64 v[244:245], v[244:245], 0, s[10:11]
	global_load_dwordx2 v[204:205], v[244:245], off
	global_load_dwordx2 v[206:207], v[244:245], off offset:32
	global_load_dwordx2 v[208:209], v[244:245], off offset:64
	global_load_dwordx2 v[236:237], v[244:245], off offset:96
	global_load_dwordx2 v[238:239], v[244:245], off offset:128
	global_load_dwordx2 v[240:241], v[244:245], off offset:160
	global_load_dwordx2 v[242:243], v[244:245], off offset:192
	global_load_dwordx2 v[244:245], v[244:245], off offset:224
	v_readlane_b32 s10, v251, 6
	v_readlane_b32 s11, v251, 7
	s_lshl_b32 s9, s9, 2
	s_add_u32 s10, s10, s12
	s_addc_u32 s11, s11, s13
	s_add_u32 s10, s10, s9
	s_addc_u32 s11, s11, 0
	s_nop 4
	global_load_dwordx4 v[232:235], v32, s[10:11]
	global_load_dwordx4 v[188:191], v32, s[10:11] offset:64
	global_load_dwordx4 v[192:195], v32, s[10:11] offset:128
	global_load_dwordx4 v[196:199], v32, s[10:11] offset:192
	global_load_dwordx4 v[200:203], v32, s[10:11] offset:256
	global_load_dwordx4 v[210:213], v32, s[10:11] offset:320
	global_load_dwordx4 v[214:217], v32, s[10:11] offset:384
	global_load_dwordx4 v[228:231], v32, s[10:11] offset:448
	s_barrier
.LBB0_1246:
	ds_read_b128 v[170:173], v169
	ds_read_b128 v[174:177], v169 offset:16
	ds_read_b128 v[178:181], v169 offset:32
	ds_read_b128 v[182:185], v169 offset:48
	s_add_i32 s2, s2, -1
	s_waitcnt lgkmcnt(3)
	v_lshlrev_b32_e32 v186, 16, v170
	v_and_b32_e32 v187, 0xffff0000, v170
	v_lshlrev_b32_e32 v170, 16, v171
	v_and_b32_e32 v171, 0xffff0000, v171
	v_pk_add_f32 v[158:159], v[158:159], v[170:171]
	v_lshlrev_b32_e32 v170, 16, v172
	v_and_b32_e32 v171, 0xffff0000, v172
	v_pk_add_f32 v[156:157], v[156:157], v[170:171]
	v_lshlrev_b32_e32 v170, 16, v173
	v_and_b32_e32 v171, 0xffff0000, v173
	v_pk_add_f32 v[154:155], v[154:155], v[170:171]
	s_waitcnt lgkmcnt(2)
	v_lshlrev_b32_e32 v170, 16, v174
	v_and_b32_e32 v171, 0xffff0000, v174
	v_pk_add_f32 v[152:153], v[152:153], v[170:171]
	v_lshlrev_b32_e32 v170, 16, v175
	v_and_b32_e32 v171, 0xffff0000, v175
	v_pk_add_f32 v[150:151], v[150:151], v[170:171]
	v_lshlrev_b32_e32 v170, 16, v176
	v_and_b32_e32 v171, 0xffff0000, v176
	v_pk_add_f32 v[148:149], v[148:149], v[170:171]
	v_lshlrev_b32_e32 v170, 16, v177
	v_and_b32_e32 v171, 0xffff0000, v177
	v_pk_add_f32 v[146:147], v[146:147], v[170:171]
	s_waitcnt lgkmcnt(1)
	v_lshlrev_b32_e32 v170, 16, v178
	v_and_b32_e32 v171, 0xffff0000, v178
	v_pk_add_f32 v[144:145], v[144:145], v[170:171]
	v_lshlrev_b32_e32 v170, 16, v179
	v_and_b32_e32 v171, 0xffff0000, v179
	v_pk_add_f32 v[142:143], v[142:143], v[170:171]
	v_lshlrev_b32_e32 v170, 16, v180
	v_and_b32_e32 v171, 0xffff0000, v180
	v_pk_add_f32 v[140:141], v[140:141], v[170:171]
	v_lshlrev_b32_e32 v170, 16, v181
	v_and_b32_e32 v171, 0xffff0000, v181
	v_pk_add_f32 v[138:139], v[138:139], v[170:171]
	s_waitcnt lgkmcnt(0)
	v_lshlrev_b32_e32 v170, 16, v182
	v_and_b32_e32 v171, 0xffff0000, v182
	v_pk_add_f32 v[136:137], v[136:137], v[170:171]
	v_lshlrev_b32_e32 v170, 16, v183
	v_and_b32_e32 v171, 0xffff0000, v183
	v_pk_add_f32 v[134:135], v[134:135], v[170:171]
	v_lshlrev_b32_e32 v170, 16, v184
	v_and_b32_e32 v171, 0xffff0000, v184
	v_pk_add_f32 v[132:133], v[132:133], v[170:171]
	v_lshlrev_b32_e32 v170, 16, v185
	v_and_b32_e32 v171, 0xffff0000, v185
	v_pk_add_f32 v[160:161], v[160:161], v[186:187]
	v_pk_add_f32 v[130:131], v[130:131], v[170:171]
	v_add_u32_e32 v169, 0xfffffef0, v169
	s_cmp_lg_u32 s2, 0
	s_cbranch_scc1 .LBB0_1246
	v_readlane_b32 s2, v253, 26
	v_add3_u32 v182, 0, v166, v167
	v_readlane_b32 s48, v251, 4
	v_add_u32_e32 v168, s2, v168
	v_readlane_b32 s2, v253, 19
	v_readlane_b32 s50, v251, 6
	v_readlane_b32 s51, v251, 7
	v_min_i32_e32 v168, s2, v168
	v_cvt_f32_i32_e32 v170, v168
	s_mov_b64 s[74:75], s[50:51]
	s_add_u32 s2, s74, s12
	s_addc_u32 s14, s75, s13
	v_div_scale_f32 v168, s[8:9], v170, v170, 1.0
	v_rcp_f32_e32 v169, v168
	v_div_scale_f32 v171, vcc, 1.0, v170, 1.0
	s_ashr_i32 s8, s17, 2
	v_fma_f32 v172, -v168, v169, 1.0
	v_fmac_f32_e32 v169, v172, v169
	v_mul_f32_e32 v172, v171, v169
	v_fma_f32 v173, -v168, v172, v171
	v_fmac_f32_e32 v172, v173, v169
	v_fma_f32 v168, -v168, v172, v171
	v_div_fmas_f32 v171, v168, v169, v172
	ds_read_b128 v[166:169], v182 offset:4080
	v_div_fixup_f32 v183, v171, v170, 1.0
	ds_read_b128 v[170:173], v182 offset:4096
	ds_read_b128 v[174:177], v182 offset:4112
	ds_read_b128 v[178:181], v182 offset:4128
	s_mov_b64 s[10:11], 0x11101000
	v_readlane_b32 s49, v251, 5
	s_waitcnt lgkmcnt(3)
	v_lshlrev_b32_e32 v184, 16, v166
	v_fma_f32 v160, v183, v160, -v184
	v_and_b32_e32 v166, 0xffff0000, v166
	v_fma_f32 v161, v183, v161, -v166
	v_cvt_pk_bf16_f32 v166, v160, v161
	v_lshlrev_b32_e32 v160, 16, v167
	v_fma_f32 v158, v183, v158, -v160
	v_and_b32_e32 v160, 0xffff0000, v167
	v_fma_f32 v159, v183, v159, -v160
	v_cvt_pk_bf16_f32 v167, v158, v159
	v_lshlrev_b32_e32 v158, 16, v168
	v_fma_f32 v156, v183, v156, -v158
	v_and_b32_e32 v158, 0xffff0000, v168
	v_fma_f32 v157, v183, v157, -v158
	v_cvt_pk_bf16_f32 v168, v156, v157
	v_lshlrev_b32_e32 v156, 16, v169
	v_fma_f32 v154, v183, v154, -v156
	v_and_b32_e32 v156, 0xffff0000, v169
	v_fma_f32 v155, v183, v155, -v156
	v_cvt_pk_bf16_f32 v169, v154, v155
	s_waitcnt lgkmcnt(2)
	v_lshlrev_b32_e32 v154, 16, v170
	v_fma_f32 v152, v183, v152, -v154
	v_and_b32_e32 v154, 0xffff0000, v170
	v_fma_f32 v153, v183, v153, -v154
	v_cvt_pk_bf16_f32 v152, v152, v153
	v_lshlrev_b32_e32 v153, 16, v171
	v_fma_f32 v150, v183, v150, -v153
	v_and_b32_e32 v153, 0xffff0000, v171
	v_fma_f32 v151, v183, v151, -v153
	v_cvt_pk_bf16_f32 v153, v150, v151
	v_lshlrev_b32_e32 v150, 16, v172
	v_fma_f32 v148, v183, v148, -v150
	v_and_b32_e32 v150, 0xffff0000, v172
	v_fma_f32 v149, v183, v149, -v150
	v_cvt_pk_bf16_f32 v154, v148, v149
	v_lshlrev_b32_e32 v148, 16, v173
	v_fma_f32 v146, v183, v146, -v148
	v_and_b32_e32 v148, 0xffff0000, v173
	v_fma_f32 v147, v183, v147, -v148
	v_cvt_pk_bf16_f32 v155, v146, v147
	s_waitcnt lgkmcnt(1)
	v_lshlrev_b32_e32 v146, 16, v174
	v_fma_f32 v144, v183, v144, -v146
	v_and_b32_e32 v146, 0xffff0000, v174
	v_fma_f32 v145, v183, v145, -v146
	v_cvt_pk_bf16_f32 v144, v144, v145
	v_lshlrev_b32_e32 v145, 16, v175
	v_fma_f32 v142, v183, v142, -v145
	v_and_b32_e32 v145, 0xffff0000, v175
	v_fma_f32 v143, v183, v143, -v145
	v_cvt_pk_bf16_f32 v145, v142, v143
	v_lshlrev_b32_e32 v142, 16, v176
	v_fma_f32 v140, v183, v140, -v142
	v_and_b32_e32 v142, 0xffff0000, v176
	v_fma_f32 v141, v183, v141, -v142
	v_cvt_pk_bf16_f32 v146, v140, v141
	v_lshlrev_b32_e32 v140, 16, v177
	v_fma_f32 v138, v183, v138, -v140
	v_and_b32_e32 v140, 0xffff0000, v177
	v_fma_f32 v139, v183, v139, -v140
	v_cvt_pk_bf16_f32 v147, v138, v139
	s_waitcnt lgkmcnt(0)
	v_lshlrev_b32_e32 v138, 16, v178
	v_fma_f32 v136, v183, v136, -v138
	v_and_b32_e32 v138, 0xffff0000, v178
	v_fma_f32 v137, v183, v137, -v138
	v_cvt_pk_bf16_f32 v136, v136, v137
	v_lshlrev_b32_e32 v137, 16, v179
	v_fma_f32 v134, v183, v134, -v137
	v_and_b32_e32 v137, 0xffff0000, v179
	v_fma_f32 v135, v183, v135, -v137
	v_cvt_pk_bf16_f32 v137, v134, v135
	v_lshlrev_b32_e32 v134, 16, v180
	v_fma_f32 v132, v183, v132, -v134
	v_and_b32_e32 v134, 0xffff0000, v180
	v_fma_f32 v133, v183, v133, -v134
	v_cvt_pk_bf16_f32 v138, v132, v133
	v_lshlrev_b32_e32 v132, 16, v181
	v_fma_f32 v130, v183, v130, -v132
	v_and_b32_e32 v132, 0xffff0000, v181
	v_fma_f32 v131, v183, v131, -v132
	v_and_or_b32 v142, s8, -16, v165
	v_cvt_pk_bf16_f32 v139, v130, v131
	v_mul_lo_u32 v130, v142, s33
	v_and_b32_e32 v131, 48, v164
	v_add3_u32 v143, 0, v130, v131
	ds_write_b128 v182, v[166:169] offset:40960
	ds_write_b128 v182, v[152:155] offset:40976
	ds_write_b128 v182, v[144:147] offset:40992
	ds_write_b128 v182, v[136:139] offset:41008
	s_waitcnt lgkmcnt(0)
	s_barrier
	ds_read_b128 v[134:137], v143 offset:40960
	ds_read_b128 v[130:133], v143 offset:41024
	s_waitcnt vmcnt(47) lgkmcnt(1)
	v_mfma_f32_16x16x32_bf16 v[122:125], v[122:125], v[134:137], 0
	v_readlane_b32 s8, v253, 30
	v_mov_b32_e32 v164, v218
	v_readlane_b32 s52, v251, 8
	s_waitcnt vmcnt(46) lgkmcnt(0)
	v_mfma_f32_16x16x32_bf16 v[138:141], v[118:121], v[130:133], v[122:125]
	s_nop 2
	ds_read_b128 v[122:125], v143 offset:41088
	ds_read_b128 v[118:121], v143 offset:41152
	v_readlane_b32 s53, v251, 9
	v_readlane_b32 s54, v251, 10
	s_waitcnt vmcnt(45) lgkmcnt(1)
	v_mfma_f32_16x16x32_bf16 v[114:117], v[114:117], v[122:125], v[138:141]
	v_readlane_b32 s55, v251, 11
	v_readlane_b32 s56, v251, 12
	v_readlane_b32 s57, v251, 13
	s_waitcnt vmcnt(44) lgkmcnt(0)
	v_mfma_f32_16x16x32_bf16 v[110:113], v[110:113], v[118:121], v[114:117]
	v_readlane_b32 s58, v251, 14
	v_readlane_b32 s59, v251, 15
	v_readlane_b32 s60, v251, 16
	s_waitcnt vmcnt(17)
	v_mfma_f32_16x16x32_bf16 v[114:117], v[126:129], v[134:137], 0
	v_readlane_b32 s61, v251, 17
	v_readlane_b32 s62, v251, 18
	v_readlane_b32 s63, v251, 19
	v_mfma_f32_16x16x32_bf16 v[106:109], v[106:109], v[130:133], v[114:117]
	v_mfma_f32_16x16x32_bf16 v[98:101], v[98:101], v[134:137], 0
	s_nop 2
	v_add_u32_e32 v114, s8, v142
	v_mfma_f32_16x16x32_bf16 v[102:105], v[102:105], v[122:125], v[106:109]
	s_nop 2
	v_mov_b64_e32 v[106:107], s[24:25]
	v_mad_i64_i32 v[106:107], s[8:9], v114, s70, v[106:107]
	v_mfma_f32_16x16x32_bf16 v[86:89], v[86:89], v[134:137], 0
	v_readlane_b32 s8, v253, 21
	s_lshl_b32 s28, s8, 1
	v_lshl_add_u64 v[106:107], v[106:107], 0, s[28:29]
	v_mfma_f32_16x16x32_bf16 v[96:99], v[94:97], v[130:133], v[98:101]
	v_lshlrev_b32_e32 v108, 3, v163
	v_mov_b32_e32 v109, v33
	s_mov_b32 s9, 0x11101000
	v_lshl_add_u64 v[100:101], v[106:107], 0, v[108:109]
	v_mfma_f32_16x16x32_bf16 v[84:87], v[82:85], v[130:133], v[86:89]
	s_lshl_b32 s8, s8, 2
	v_lshl_add_u64 v[94:95], v[100:101], 0, s[10:11]
	s_add_u32 s10, s2, s8
	v_mfma_f32_16x16x32_bf16 v[90:93], v[90:93], v[122:125], v[96:99]
	s_addc_u32 s11, s14, 0
	v_readlane_b32 s8, v253, 28
	s_or_b32 s8, s8, s16
	v_add_co_u32_e32 v96, vcc, s9, v100
	v_mfma_f32_16x16x32_bf16 v[78:81], v[78:81], v[122:125], v[84:87]
	s_nop 0
	v_addc_co_u32_e32 v97, vcc, 0, v101, vcc
	s_waitcnt vmcnt(0)
	s_nop 15
	v_mov_b64_e32 v[98:99], v[206:207]
	v_mov_b64_e32 v[100:101], v[208:209]
	v_mov_b64_e32 v[106:107], v[236:237]
	v_mov_b64_e32 v[108:109], v[238:239]
	v_mov_b64_e32 v[88:89], v[204:205]
	v_mov_b64_e32 v[114:115], v[240:241]
	v_mov_b64_e32 v[116:117], v[242:243]
	v_mov_b64_e32 v[82:83], v[244:245]
	s_nop 15
	v_mov_b64_e32 v[84:85], v[232:233]
	v_mov_b64_e32 v[86:87], v[234:235]
	v_mfma_f32_16x16x32_bf16 v[74:77], v[74:77], v[134:137], 0
	v_readlane_b32 s9, v252, 29
	s_add_u32 s8, s9, s8
	v_readlane_b32 s9, v252, 30
	v_mfma_f32_16x16x32_bf16 v[62:65], v[62:65], v[134:137], 0
	s_addc_u32 s9, s9, 0
	v_mfma_f32_16x16x32_bf16 v[70:73], v[70:73], v[130:133], v[74:77]
	v_mfma_f32_16x16x32_bf16 v[58:61], v[58:61], v[130:133], v[62:65]
	s_waitcnt vmcnt(4)
	s_nop 0
	v_lshlrev_b32_e32 v75, 16, v88
	v_mfma_f32_16x16x32_bf16 v[66:69], v[66:69], v[122:125], v[70:73]
	s_nop 0
	v_and_b32_e32 v64, 0xffff0000, v89
	s_waitcnt vmcnt(0)
	v_mul_f32_e32 v74, v110, v84
	v_mul_f32_e32 v70, v111, v85
	v_and_b32_e32 v71, 0xffff0000, v88
	v_mul_f32_e32 v70, v70, v71
	v_mul_f32_e32 v71, v112, v86
	v_lshlrev_b32_e32 v72, 16, v89
	v_mul_f32_e32 v63, v113, v87
	v_mul_f32_e32 v74, v74, v75
	v_cvt_pk_bf16_f32 v70, v74, v70
	v_mul_f32_e32 v62, v71, v72
	v_mfma_f32_16x16x32_bf16 v[54:57], v[54:57], v[122:125], v[58:61]
	s_nop 2
	v_mul_f32_e32 v58, v63, v64
	v_cvt_pk_bf16_f32 v71, v62, v58
	global_store_dwordx2 v[96:97], v[70:71], off
	v_mov_b64_e32 v[58:59], v[188:189]
	v_mov_b64_e32 v[60:61], v[190:191]
	v_mfma_f32_16x16x32_bf16 v[50:53], v[50:53], v[134:137], 0
	v_lshlrev_b32_e32 v62, 16, v98
	v_mfma_f32_16x16x32_bf16 v[28:31], v[28:31], v[118:121], v[102:105]
	v_mfma_f32_16x16x32_bf16 v[46:49], v[46:49], v[130:133], v[50:53]
	v_mfma_f32_16x16x32_bf16 v[42:45], v[42:45], v[122:125], v[46:49]
	s_nop 4
	v_mul_f32_e32 v28, v28, v58
	v_mul_f32_e32 v29, v29, v59
	v_and_b32_e32 v58, 0xffff0000, v98
	v_mul_f32_e32 v28, v28, v62
	v_mul_f32_e32 v29, v29, v58
	v_cvt_pk_bf16_f32 v50, v28, v29
	v_mul_f32_e32 v28, v30, v60
	v_lshlrev_b32_e32 v29, 16, v99
	v_mul_f32_e32 v46, v28, v29
	v_mul_f32_e32 v47, v31, v61
	v_mfma_f32_16x16x32_bf16 v[28:31], v[38:41], v[134:137], 0
	v_and_b32_e32 v48, 0xffff0000, v99
	v_mul_f32_e32 v38, v47, v48
	v_cvt_pk_bf16_f32 v51, v46, v38
	global_store_dwordx2 v[94:95], v[50:51], off offset:32
	v_mfma_f32_16x16x32_bf16 v[28:31], v[34:37], v[130:133], v[28:31]
	v_mov_b64_e32 v[34:35], v[192:193]
	v_mov_b64_e32 v[36:37], v[194:195]
	v_lshlrev_b32_e32 v38, 16, v100
	v_and_b32_e32 v39, 0xffff0000, v100
	v_mfma_f32_16x16x32_bf16 v[24:27], v[24:27], v[118:121], v[90:93]
	v_lshlrev_b32_e32 v40, 16, v101
	v_and_b32_e32 v41, 0xffff0000, v101
	v_mov_b32_e32 v131, v33
	v_mfma_f32_16x16x32_bf16 v[16:19], v[16:19], v[118:121], v[78:81]
	v_mfma_f32_16x16x32_bf16 v[20:23], v[20:23], v[118:121], v[66:69]
	s_nop 1
	v_mul_f32_e32 v24, v24, v34
	v_mul_f32_e32 v25, v25, v35
	v_mul_f32_e32 v26, v26, v36
	v_mul_f32_e32 v27, v27, v37
	v_mul_f32_e32 v24, v24, v38
	v_mul_f32_e32 v25, v25, v39
	v_mul_f32_e32 v26, v26, v40
	v_mul_f32_e32 v27, v27, v41
	v_cvt_pk_bf16_f32 v24, v24, v25
	v_cvt_pk_bf16_f32 v25, v26, v27
	global_store_dwordx2 v[94:95], v[24:25], off offset:64
	v_mov_b64_e32 v[24:25], v[196:197]
	v_mov_b64_e32 v[26:27], v[198:199]
	v_lshlrev_b32_e32 v34, 16, v106
	v_and_b32_e32 v35, 0xffff0000, v106
	v_lshlrev_b32_e32 v36, 16, v107
	v_and_b32_e32 v37, 0xffff0000, v107
	v_mfma_f32_16x16x32_bf16 v[12:15], v[12:15], v[118:121], v[54:57]
	v_mul_f32_e32 v16, v16, v24
	v_mul_f32_e32 v17, v17, v25
	v_mul_f32_e32 v18, v18, v26
	v_mul_f32_e32 v19, v19, v27
	v_mul_f32_e32 v16, v16, v34
	v_mul_f32_e32 v17, v17, v35
	v_mul_f32_e32 v18, v18, v36
	v_mul_f32_e32 v19, v19, v37
	v_cvt_pk_bf16_f32 v16, v16, v17
	v_cvt_pk_bf16_f32 v17, v18, v19
	global_store_dwordx2 v[94:95], v[16:17], off offset:96
	v_mov_b64_e32 v[16:17], v[200:201]
	v_mov_b64_e32 v[18:19], v[202:203]
	v_lshlrev_b32_e32 v24, 16, v108
	v_and_b32_e32 v25, 0xffff0000, v108
	v_lshlrev_b32_e32 v26, 16, v109
	v_and_b32_e32 v27, 0xffff0000, v109
	v_mfma_f32_16x16x32_bf16 v[8:11], v[8:11], v[118:121], v[42:45]
	v_mul_f32_e32 v16, v20, v16
	v_mul_f32_e32 v17, v21, v17
	v_mul_f32_e32 v18, v22, v18
	v_mul_f32_e32 v19, v23, v19
	v_mul_f32_e32 v16, v16, v24
	v_mul_f32_e32 v17, v17, v25
	v_mul_f32_e32 v18, v18, v26
	v_mul_f32_e32 v19, v19, v27
	v_cvt_pk_bf16_f32 v16, v16, v17
	v_cvt_pk_bf16_f32 v17, v18, v19
	global_store_dwordx2 v[94:95], v[16:17], off offset:128
	v_mov_b64_e32 v[16:17], v[210:211]
	v_mov_b64_e32 v[18:19], v[212:213]
	v_lshlrev_b32_e32 v20, 16, v114
	v_and_b32_e32 v21, 0xffff0000, v114
	v_lshlrev_b32_e32 v22, 16, v115
	v_and_b32_e32 v23, 0xffff0000, v115
	v_mfma_f32_16x16x32_bf16 v[4:7], v[4:7], v[122:125], v[28:31]
	v_mul_f32_e32 v12, v12, v16
	v_mul_f32_e32 v13, v13, v17
	v_mul_f32_e32 v14, v14, v18
	v_mul_f32_e32 v15, v15, v19
	v_mul_f32_e32 v12, v12, v20
	v_mul_f32_e32 v13, v13, v21
	v_mul_f32_e32 v14, v14, v22
	v_mul_f32_e32 v15, v15, v23
	v_cvt_pk_bf16_f32 v12, v12, v13
	v_cvt_pk_bf16_f32 v13, v14, v15
	global_store_dwordx2 v[94:95], v[12:13], off offset:160
	v_mov_b64_e32 v[12:13], v[214:215]
	v_mov_b64_e32 v[14:15], v[216:217]
	v_lshlrev_b32_e32 v16, 16, v116
	v_and_b32_e32 v17, 0xffff0000, v116
	v_lshlrev_b32_e32 v18, 16, v117
	v_and_b32_e32 v19, 0xffff0000, v117
	v_mfma_f32_16x16x32_bf16 v[0:3], v[0:3], v[118:121], v[4:7]
	v_mul_f32_e32 v8, v8, v12
	v_mul_f32_e32 v9, v9, v13
	v_mul_f32_e32 v10, v10, v14
	v_mul_f32_e32 v11, v11, v15
	v_mul_f32_e32 v8, v8, v16
	v_mul_f32_e32 v9, v9, v17
	v_mul_f32_e32 v10, v10, v18
	v_mul_f32_e32 v11, v11, v19
	v_cvt_pk_bf16_f32 v8, v8, v9
	v_cvt_pk_bf16_f32 v9, v10, v11
	global_store_dwordx2 v[94:95], v[8:9], off offset:192
	v_mov_b64_e32 v[8:9], v[228:229]
	v_mov_b64_e32 v[10:11], v[230:231]
	v_lshlrev_b32_e32 v4, 16, v82
	v_and_b32_e32 v5, 0xffff0000, v82
	v_lshlrev_b32_e32 v6, 16, v83
	v_and_b32_e32 v7, 0xffff0000, v83
	v_mul_f32_e32 v0, v0, v8
	v_mul_f32_e32 v1, v1, v9
	v_mul_f32_e32 v2, v2, v10
	v_mul_f32_e32 v3, v3, v11
	v_mul_f32_e32 v0, v0, v4
	v_mul_f32_e32 v1, v1, v5
	v_mul_f32_e32 v2, v2, v6
	v_mul_f32_e32 v3, v3, v7
	v_cvt_pk_bf16_f32 v0, v0, v1
	v_cvt_pk_bf16_f32 v1, v2, v3
	global_store_dwordx2 v[94:95], v[0:1], off offset:224
	s_barrier
	s_nop 0
	v_and_b32_e32 v165, 15, v164
	v_bfe_u32 v163, v164, 4, 2
	v_lshlrev_b32_e32 v32, 8, v165
	v_lshl_add_u64 v[0:1], s[8:9], 0, v[32:33]
	v_lshlrev_b32_e32 v32, 4, v163
	v_lshl_add_u64 v[0:1], v[0:1], 0, v[32:33]
	v_readlane_b32 s8, v253, 35
	v_readlane_b32 s9, v253, 36
	v_lshlrev_b32_e32 v130, 4, v165
	v_mov_b32_e32 v131, v33
	s_nop 1
	v_lshl_add_u64 v[136:137], s[8:9], 0, v[130:131]
	v_add_u32_e32 v134, 0, v130
	s_movk_i32 s8, 0x8f0
	v_cmp_gt_i32_e32 vcc, s8, v164
	s_and_saveexec_b64 s[10:11], vcc
	v_readlane_b32 s86, v254, 59
	v_readlane_b32 s84, v254, 61
	v_readlane_b32 s87, v254, 60
	v_readlane_b32 s85, v254, 62
	s_cbranch_execz .LBB0_1251
	v_ashrrev_i32_e32 v135, 4, v164
	v_readlane_b32 s8, v253, 38
	v_mov_b32_e32 v232, 0
	v_mov_b32_e32 v233, 0
	v_cmp_lt_i32_e32 vcc, s8, v135
	v_mov_b32_e32 v234, 0
	v_mov_b32_e32 v235, 0
	s_and_saveexec_b64 s[12:13], vcc
	s_cbranch_execz .LBB0_1250
	v_readlane_b32 s8, v253, 37
	s_nop 1
	v_add_u32_e32 v232, s8, v135
	v_mad_i64_i32 v[232:233], s[8:9], v232, s70, v[136:137]
	global_load_dwordx4 v[232:235], v[232:233], off

.LBB0_1267:
	s_or_b64 exec, exec, s[10:11]
	s_movk_i32 s8, 0x1000
	v_add_co_u32_e32 v2, vcc, s8, v0
	s_movk_i32 s8, 0x3000
	s_nop 0
	v_addc_co_u32_e32 v3, vcc, 0, v1, vcc
	v_add_co_u32_e32 v12, vcc, s1, v0
	global_load_dwordx4 v[114:117], v[0:1], off
	global_load_dwordx4 v[110:113], v[0:1], off offset:64
	global_load_dwordx4 v[106:109], v[0:1], off offset:128
	global_load_dwordx4 v[102:105], v[0:1], off offset:192
	v_addc_co_u32_e32 v13, vcc, 0, v1, vcc
	v_add_co_u32_e32 v4, vcc, s8, v0
	s_movk_i32 s8, 0x4000
	s_nop 0
	v_addc_co_u32_e32 v5, vcc, 0, v1, vcc
	v_add_co_u32_e32 v6, vcc, s8, v0
	s_movk_i32 s8, 0x5000
	s_nop 0
	v_addc_co_u32_e32 v7, vcc, 0, v1, vcc
	global_load_dwordx4 v[122:125], v[2:3], off offset:64
	global_load_dwordx4 v[118:121], v[2:3], off offset:128
	global_load_dwordx4 v[98:101], v[12:13], off
	global_load_dwordx4 v[94:97], v[12:13], off offset:64
	global_load_dwordx4 v[90:93], v[12:13], off offset:128
	global_load_dwordx4 v[20:23], v[12:13], off offset:192
	global_load_dwordx4 v[38:41], v[2:3], off offset:192
	global_load_dwordx4 v[78:81], v[4:5], off offset:64
	global_load_dwordx4 v[74:77], v[4:5], off offset:128
	global_load_dwordx4 v[16:19], v[4:5], off offset:192
	global_load_dwordx4 v[82:85], v[6:7], off offset:-4096
	global_load_dwordx4 v[70:73], v[6:7], off
	global_load_dwordx4 v[66:69], v[6:7], off offset:64
	global_load_dwordx4 v[58:61], v[6:7], off offset:128
	v_add_co_u32_e32 v8, vcc, s8, v0
	s_movk_i32 s8, 0x6000
	s_nop 0
	v_addc_co_u32_e32 v9, vcc, 0, v1, vcc
	v_add_co_u32_e32 v2, vcc, s8, v0
	global_load_dwordx4 v[62:65], v[8:9], off offset:64
	global_load_dwordx4 v[50:53], v[8:9], off offset:128
	v_addc_co_u32_e32 v3, vcc, 0, v1, vcc
	v_add_co_u32_e32 v14, vcc, 0x7000, v0
	global_load_dwordx4 v[34:37], v[6:7], off offset:192
	global_load_dwordx4 v[86:89], v[2:3], off offset:-4096
	global_load_dwordx4 v[54:57], v[2:3], off
	global_load_dwordx4 v[46:49], v[2:3], off offset:64
	global_load_dwordx4 v[42:45], v[2:3], off offset:128
	global_load_dwordx4 v[24:27], v[2:3], off offset:192
	v_addc_co_u32_e32 v15, vcc, 0, v1, vcc
	global_load_dwordx4 v[28:31], v[8:9], off offset:192
	s_nop 0
	global_load_dwordx4 v[8:11], v[14:15], off
	global_load_dwordx4 v[4:7], v[14:15], off offset:64
	global_load_dwordx4 v[0:3], v[14:15], off offset:128
	global_load_dwordx4 v[126:129], v[12:13], off offset:-4096
	s_nop 0
	global_load_dwordx4 v[12:15], v[14:15], off offset:192
	v_readlane_b32 s8, v253, 35
	v_lshlrev_b32_e32 v130, 4, v165
	v_readlane_b32 s9, v253, 36
	v_readfirstlane_b32 s15, v164
	v_add_u32_e32 v134, 0, v130
	v_lshl_add_u64 v[136:137], s[8:9], 0, v[130:131]
	s_movk_i32 s8, 0x8f0
	s_waitcnt vmcnt(32)
	s_movk_i32 s8, 0x8f0
	v_cmp_gt_i32_e32 vcc, s8, v164
	s_and_saveexec_b64 s[10:11], vcc
	ds_write_b128 v204, v[232:235]
	s_or_b64 exec, exec, s[10:11]
	s_movk_i32 s8, 0x6f0
	v_cmp_gt_i32_e32 vcc, s8, v164
	s_and_saveexec_b64 s[10:11], vcc
	ds_write_b128 v205, v[188:191]
	s_or_b64 exec, exec, s[10:11]
	s_movk_i32 s8, 0x4f0
	v_cmp_gt_i32_e32 vcc, s8, v164
	s_and_saveexec_b64 s[10:11], vcc
	ds_write_b128 v206, v[192:195]
	s_or_b64 exec, exec, s[10:11]
	s_movk_i32 s8, 0x2f0
	v_cmp_gt_i32_e32 vcc, s8, v164
	s_and_saveexec_b64 s[10:11], vcc
	ds_write_b128 v207, v[196:199]
	s_or_b64 exec, exec, s[10:11]
	s_movk_i32 s8, 0xf0
	v_cmp_gt_i32_e32 vcc, s8, v164
	s_and_saveexec_b64 s[10:11], vcc
	ds_write_b128 v208, v[200:203]
	s_or_b64 exec, exec, s[10:11]
	v_ashrrev_i32_e32 v168, 2, v164
	v_lshlrev_b32_e32 v130, 6, v164
	v_mul_lo_u32 v166, v168, s33
	v_and_b32_e32 v167, 0xc0, v130
	v_readlane_b32 s8, v254, 56
	v_mov_b32_e32 v130, 0
	v_mov_b32_e32 v131, v130
	v_add3_u32 v169, v166, v167, s8
	v_readlane_b32 s8, v253, 27
	v_mov_b32_e32 v160, v130
	v_mov_b32_e32 v161, v130
	v_mov_b32_e32 v158, v130
	v_mov_b32_e32 v159, v130
	v_mov_b32_e32 v156, v130
	v_mov_b32_e32 v157, v130
	v_mov_b32_e32 v154, v130
	v_mov_b32_e32 v155, v130
	v_mov_b32_e32 v152, v130
	v_mov_b32_e32 v153, v130
	v_mov_b32_e32 v150, v130
	v_mov_b32_e32 v151, v130
	v_mov_b32_e32 v148, v130
	v_mov_b32_e32 v149, v130
	v_mov_b32_e32 v146, v130
	v_mov_b32_e32 v147, v130
	v_mov_b32_e32 v144, v130
	v_mov_b32_e32 v145, v130
	v_mov_b32_e32 v142, v130
	v_mov_b32_e32 v143, v130
	v_mov_b32_e32 v140, v130
	v_mov_b32_e32 v141, v130
	v_mov_b32_e32 v138, v130
	v_mov_b32_e32 v139, v130
	v_mov_b32_e32 v136, v130
	v_mov_b32_e32 v137, v130
	v_mov_b32_e32 v134, v130
	v_mov_b32_e32 v135, v130
	v_mov_b32_e32 v132, v130
	v_mov_b32_e32 v133, v130
	s_waitcnt lgkmcnt(0)
	s_ashr_i32 s9, s15, 2
	v_and_or_b32 v227, s9, -16, v165
	v_readlane_b32 s9, v253, 32
	v_mov_b64_e32 v[244:245], s[24:25]
	v_lshlrev_b32_e32 v222, 3, v163
	s_nop 1
	v_add_u32_e32 v227, s9, v227
	v_add_co_u32_e32 v244, vcc, v244, v222
	v_readlane_b32 s9, v253, 29
	s_nop 1
	v_addc_co_u32_e32 v245, vcc, 0, v245, vcc
	s_nop 1
	v_mad_i64_i32 v[244:245], s[12:13], v227, s70, v[244:245]
	s_lshl_b32 s10, s9, 1
	s_add_u32 s10, s10, 0x11101000
	s_mov_b32 s11, 0
	v_lshl_add_u64 v[244:245], v[244:245], 0, s[10:11]
	global_load_dwordx2 v[204:205], v[244:245], off
	global_load_dwordx2 v[206:207], v[244:245], off offset:32
	global_load_dwordx2 v[208:209], v[244:245], off offset:64
	global_load_dwordx2 v[236:237], v[244:245], off offset:96
	global_load_dwordx2 v[238:239], v[244:245], off offset:128
	global_load_dwordx2 v[240:241], v[244:245], off offset:160
	global_load_dwordx2 v[242:243], v[244:245], off offset:192
	global_load_dwordx2 v[244:245], v[244:245], off offset:224
	s_lshl_b32 s9, s9, 2
	s_add_u32 s10, s2, s9
	s_addc_u32 s11, s14, 0
	s_nop 4
	global_load_dwordx4 v[232:235], v32, s[10:11]
	global_load_dwordx4 v[188:191], v32, s[10:11] offset:64
	global_load_dwordx4 v[192:195], v32, s[10:11] offset:128
	global_load_dwordx4 v[196:199], v32, s[10:11] offset:192
	global_load_dwordx4 v[200:203], v32, s[10:11] offset:256
	global_load_dwordx4 v[210:213], v32, s[10:11] offset:320
	global_load_dwordx4 v[214:217], v32, s[10:11] offset:384
	global_load_dwordx4 v[228:231], v32, s[10:11] offset:448
	s_barrier
.LBB0_1268:
	ds_read_b128 v[170:173], v169
	ds_read_b128 v[174:177], v169 offset:16
	ds_read_b128 v[178:181], v169 offset:32
	ds_read_b128 v[182:185], v169 offset:48
	s_add_i32 s8, s8, -1
	s_waitcnt lgkmcnt(3)
	v_lshlrev_b32_e32 v186, 16, v170
	v_and_b32_e32 v187, 0xffff0000, v170
	v_lshlrev_b32_e32 v170, 16, v171
	v_and_b32_e32 v171, 0xffff0000, v171
	v_pk_add_f32 v[158:159], v[158:159], v[170:171]
	v_lshlrev_b32_e32 v170, 16, v172
	v_and_b32_e32 v171, 0xffff0000, v172
	v_pk_add_f32 v[156:157], v[156:157], v[170:171]
	v_lshlrev_b32_e32 v170, 16, v173
	v_and_b32_e32 v171, 0xffff0000, v173
	v_pk_add_f32 v[154:155], v[154:155], v[170:171]
	s_waitcnt lgkmcnt(2)
	v_lshlrev_b32_e32 v170, 16, v174
	v_and_b32_e32 v171, 0xffff0000, v174
	v_pk_add_f32 v[152:153], v[152:153], v[170:171]
	v_lshlrev_b32_e32 v170, 16, v175
	v_and_b32_e32 v171, 0xffff0000, v175
	v_pk_add_f32 v[150:151], v[150:151], v[170:171]
	v_lshlrev_b32_e32 v170, 16, v176
	v_and_b32_e32 v171, 0xffff0000, v176
	v_pk_add_f32 v[148:149], v[148:149], v[170:171]
	v_lshlrev_b32_e32 v170, 16, v177
	v_and_b32_e32 v171, 0xffff0000, v177
	v_pk_add_f32 v[146:147], v[146:147], v[170:171]
	s_waitcnt lgkmcnt(1)
	v_lshlrev_b32_e32 v170, 16, v178
	v_and_b32_e32 v171, 0xffff0000, v178
	v_pk_add_f32 v[144:145], v[144:145], v[170:171]
	v_lshlrev_b32_e32 v170, 16, v179
	v_and_b32_e32 v171, 0xffff0000, v179
	v_pk_add_f32 v[142:143], v[142:143], v[170:171]
	v_lshlrev_b32_e32 v170, 16, v180
	v_and_b32_e32 v171, 0xffff0000, v180
	v_pk_add_f32 v[140:141], v[140:141], v[170:171]
	v_lshlrev_b32_e32 v170, 16, v181
	v_and_b32_e32 v171, 0xffff0000, v181
	v_pk_add_f32 v[138:139], v[138:139], v[170:171]
	s_waitcnt lgkmcnt(0)
	v_lshlrev_b32_e32 v170, 16, v182
	v_and_b32_e32 v171, 0xffff0000, v182
	v_pk_add_f32 v[136:137], v[136:137], v[170:171]
	v_lshlrev_b32_e32 v170, 16, v183
	v_and_b32_e32 v171, 0xffff0000, v183
	v_pk_add_f32 v[134:135], v[134:135], v[170:171]
	v_lshlrev_b32_e32 v170, 16, v184
	v_and_b32_e32 v171, 0xffff0000, v184
	v_pk_add_f32 v[132:133], v[132:133], v[170:171]
	v_lshlrev_b32_e32 v170, 16, v185
	v_and_b32_e32 v171, 0xffff0000, v185
	v_pk_add_f32 v[160:161], v[160:161], v[186:187]
	v_pk_add_f32 v[130:131], v[130:131], v[170:171]
	v_add_u32_e32 v169, 0xfffffef0, v169
	s_cmp_lg_u32 s8, 0
	s_cbranch_scc1 .LBB0_1268
	v_readlane_b32 s8, v253, 39
	v_add3_u32 v182, 0, v166, v167
	s_mov_b64 s[10:11], 0x11101000
	v_add_u32_e32 v168, s8, v168
	v_readlane_b32 s8, v253, 27
	s_mov_b32 s72, 0
	s_nop 0
	v_min_i32_e32 v168, s8, v168
	v_cvt_f32_i32_e32 v170, v168
	ds_read_b128 v[166:169], v182 offset:4080
	v_div_scale_f32 v171, s[8:9], v170, v170, 1.0
	v_rcp_f32_e32 v172, v171
	v_div_scale_f32 v173, vcc, 1.0, v170, 1.0
	s_waitcnt lgkmcnt(0)
	v_lshlrev_b32_e32 v184, 16, v166
	v_fma_f32 v174, -v171, v172, 1.0
	v_fmac_f32_e32 v172, v174, v172
	v_mul_f32_e32 v174, v173, v172
	v_fma_f32 v175, -v171, v174, v173
	v_fmac_f32_e32 v174, v175, v172
	v_fma_f32 v171, -v171, v174, v173
	v_div_fmas_f32 v171, v171, v172, v174
	v_div_fixup_f32 v183, v171, v170, 1.0
	v_fma_f32 v160, v183, v160, -v184
	v_and_b32_e32 v166, 0xffff0000, v166
	v_fma_f32 v161, v183, v161, -v166
	v_cvt_pk_bf16_f32 v166, v160, v161
	v_lshlrev_b32_e32 v160, 16, v167
	v_fma_f32 v158, v183, v158, -v160
	v_and_b32_e32 v160, 0xffff0000, v167
	v_fma_f32 v159, v183, v159, -v160
	v_cvt_pk_bf16_f32 v167, v158, v159
	v_lshlrev_b32_e32 v158, 16, v168
	ds_read_b128 v[170:173], v182 offset:4096
	ds_read_b128 v[174:177], v182 offset:4112
	ds_read_b128 v[178:181], v182 offset:4128
	v_fma_f32 v156, v183, v156, -v158
	v_and_b32_e32 v158, 0xffff0000, v168
	v_fma_f32 v157, v183, v157, -v158
	v_cvt_pk_bf16_f32 v168, v156, v157
	v_lshlrev_b32_e32 v156, 16, v169
	v_fma_f32 v154, v183, v154, -v156
	v_and_b32_e32 v156, 0xffff0000, v169
	v_fma_f32 v155, v183, v155, -v156
	v_cvt_pk_bf16_f32 v169, v154, v155
	s_waitcnt lgkmcnt(2)
	v_lshlrev_b32_e32 v154, 16, v170
	v_fma_f32 v152, v183, v152, -v154
	v_and_b32_e32 v154, 0xffff0000, v170
	v_fma_f32 v153, v183, v153, -v154
	v_cvt_pk_bf16_f32 v152, v152, v153
	v_lshlrev_b32_e32 v153, 16, v171
	v_fma_f32 v150, v183, v150, -v153
	v_and_b32_e32 v153, 0xffff0000, v171
	v_fma_f32 v151, v183, v151, -v153
	v_cvt_pk_bf16_f32 v153, v150, v151
	v_lshlrev_b32_e32 v150, 16, v172
	v_fma_f32 v148, v183, v148, -v150
	v_and_b32_e32 v150, 0xffff0000, v172
	v_fma_f32 v149, v183, v149, -v150
	v_cvt_pk_bf16_f32 v154, v148, v149
	v_lshlrev_b32_e32 v148, 16, v173
	v_fma_f32 v146, v183, v146, -v148
	v_and_b32_e32 v148, 0xffff0000, v173
	v_fma_f32 v147, v183, v147, -v148
	v_cvt_pk_bf16_f32 v155, v146, v147
	s_waitcnt lgkmcnt(1)
	v_lshlrev_b32_e32 v146, 16, v174
	v_fma_f32 v144, v183, v144, -v146
	v_and_b32_e32 v146, 0xffff0000, v174
	v_fma_f32 v145, v183, v145, -v146
	v_cvt_pk_bf16_f32 v144, v144, v145
	v_lshlrev_b32_e32 v145, 16, v175
	v_fma_f32 v142, v183, v142, -v145
	v_and_b32_e32 v145, 0xffff0000, v175
	v_fma_f32 v143, v183, v143, -v145
	v_cvt_pk_bf16_f32 v145, v142, v143
	v_lshlrev_b32_e32 v142, 16, v176
	v_fma_f32 v140, v183, v140, -v142
	v_and_b32_e32 v142, 0xffff0000, v176
	v_fma_f32 v141, v183, v141, -v142
	v_cvt_pk_bf16_f32 v146, v140, v141
	v_lshlrev_b32_e32 v140, 16, v177
	v_fma_f32 v138, v183, v138, -v140
	v_and_b32_e32 v140, 0xffff0000, v177
	v_fma_f32 v139, v183, v139, -v140
	v_cvt_pk_bf16_f32 v147, v138, v139
	s_waitcnt lgkmcnt(0)
	v_lshlrev_b32_e32 v138, 16, v178
	v_fma_f32 v136, v183, v136, -v138
	v_and_b32_e32 v138, 0xffff0000, v178
	v_fma_f32 v137, v183, v137, -v138
	v_cvt_pk_bf16_f32 v136, v136, v137
	v_lshlrev_b32_e32 v137, 16, v179
	v_fma_f32 v134, v183, v134, -v137
	v_and_b32_e32 v137, 0xffff0000, v179
	v_fma_f32 v135, v183, v135, -v137
	v_cvt_pk_bf16_f32 v137, v134, v135
	v_lshlrev_b32_e32 v134, 16, v180
	v_fma_f32 v132, v183, v132, -v134
	v_and_b32_e32 v134, 0xffff0000, v180
	v_fma_f32 v133, v183, v133, -v134
	v_cvt_pk_bf16_f32 v138, v132, v133
	v_lshlrev_b32_e32 v132, 16, v181
	v_fma_f32 v130, v183, v130, -v132
	v_and_b32_e32 v132, 0xffff0000, v181
	s_ashr_i32 s8, s15, 2
	v_fma_f32 v131, v183, v131, -v132
	v_and_or_b32 v142, s8, -16, v165
	v_cvt_pk_bf16_f32 v139, v130, v131
	v_mul_lo_u32 v130, v142, s33
	v_and_b32_e32 v131, 48, v164
	v_add3_u32 v143, 0, v130, v131
	ds_write_b128 v182, v[166:169] offset:40960
	ds_write_b128 v182, v[152:155] offset:40976
	ds_write_b128 v182, v[144:147] offset:40992
	ds_write_b128 v182, v[136:139] offset:41008
	s_waitcnt lgkmcnt(0)
	s_barrier
	ds_read_b128 v[134:137], v143 offset:40960
	ds_read_b128 v[130:133], v143 offset:41024
	s_waitcnt vmcnt(47) lgkmcnt(1)
	v_mfma_f32_16x16x32_bf16 v[114:117], v[114:117], v[134:137], 0
	v_readlane_b32 s8, v253, 32
	s_waitcnt vmcnt(46) lgkmcnt(0)
	v_mfma_f32_16x16x32_bf16 v[138:141], v[110:113], v[130:133], v[114:117]
	s_nop 4
	ds_read_b128 v[114:117], v143 offset:41088
	ds_read_b128 v[110:113], v143 offset:41152
	s_waitcnt vmcnt(45) lgkmcnt(1)
	v_mfma_f32_16x16x32_bf16 v[106:109], v[106:109], v[114:117], v[138:141]
	s_waitcnt vmcnt(44) lgkmcnt(0)
	v_mfma_f32_16x16x32_bf16 v[102:105], v[102:105], v[110:113], v[106:109]
	s_waitcnt vmcnt(17)
	v_mfma_f32_16x16x32_bf16 v[106:109], v[126:129], v[134:137], 0
	v_add_u32_e32 v126, s8, v142
	v_mfma_f32_16x16x32_bf16 v[106:109], v[122:125], v[130:133], v[106:109]
	v_mov_b64_e32 v[122:123], s[24:25]
	v_mad_i64_i32 v[122:123], s[8:9], v126, s70, v[122:123]
	v_mfma_f32_16x16x32_bf16 v[106:109], v[118:121], v[114:117], v[106:109]
	v_readlane_b32 s8, v253, 29
	s_lshl_b32 s28, s8, 1
	v_lshl_add_u64 v[122:123], v[122:123], 0, s[28:29]
	v_mfma_f32_16x16x32_bf16 v[118:121], v[98:101], v[134:137], 0
	v_lshlrev_b32_e32 v124, 3, v163
	v_mov_b32_e32 v125, v33
	v_lshl_add_u64 v[100:101], v[122:123], 0, v[124:125]
	v_mfma_f32_16x16x32_bf16 v[94:97], v[94:97], v[130:133], v[118:121]
	s_mov_b32 s9, 0x11101000
	v_lshl_add_u64 v[98:99], v[100:101], 0, s[10:11]
	v_add_co_u32_e32 v100, vcc, s9, v100
	v_mfma_f32_16x16x32_bf16 v[90:93], v[90:93], v[114:117], v[94:97]
	s_lshl_b32 s8, s8, 2
	v_addc_co_u32_e32 v101, vcc, 0, v101, vcc
	v_mfma_f32_16x16x32_bf16 v[94:97], v[82:85], v[134:137], 0
	s_add_u32 s10, s2, s8
	s_waitcnt vmcnt(0)
	s_nop 15
	v_mov_b64_e32 v[118:119], v[206:207]
	v_mov_b64_e32 v[120:121], v[208:209]
	v_mov_b64_e32 v[122:123], v[236:237]
	v_mov_b64_e32 v[124:125], v[238:239]
	v_mov_b64_e32 v[84:85], v[204:205]
	v_mov_b64_e32 v[126:127], v[240:241]
	v_mov_b64_e32 v[128:129], v[242:243]
	v_mov_b64_e32 v[82:83], v[244:245]
	v_mfma_f32_16x16x32_bf16 v[78:81], v[78:81], v[130:133], v[94:97]
	s_addc_u32 s11, s14, 0
	s_lshl_b32 s8, s18, 11
	v_mfma_f32_16x16x32_bf16 v[74:77], v[74:77], v[114:117], v[78:81]
	s_mov_b32 s2, 0
	s_waitcnt vmcnt(3)
	v_lshlrev_b32_e32 v94, 16, v84
	s_nop 1
	s_nop 15
	v_mov_b64_e32 v[78:79], v[232:233]
	v_mov_b64_e32 v[80:81], v[234:235]
	v_mfma_f32_16x16x32_bf16 v[70:73], v[70:73], v[134:137], 0
	s_waitcnt vmcnt(0)
	v_mul_f32_e32 v78, v102, v78
	v_mfma_f32_16x16x32_bf16 v[66:69], v[66:69], v[130:133], v[70:73]
	v_mul_f32_e32 v78, v78, v94
	v_mfma_f32_16x16x32_bf16 v[58:61], v[58:61], v[114:117], v[66:69]
	s_nop 2
	v_mul_f32_e32 v70, v103, v79
	v_and_b32_e32 v71, 0xffff0000, v84
	v_mul_f32_e32 v70, v70, v71
	v_mfma_f32_16x16x32_bf16 v[66:69], v[86:89], v[134:137], 0
	v_mul_f32_e32 v71, v104, v80
	v_lshlrev_b32_e32 v72, 16, v85
	v_mul_f32_e32 v71, v71, v72
	v_mfma_f32_16x16x32_bf16 v[62:65], v[62:65], v[130:133], v[66:69]
	v_mul_f32_e32 v72, v105, v81
	v_and_b32_e32 v73, 0xffff0000, v85
	v_cvt_pk_bf16_f32 v70, v78, v70
	v_mfma_f32_16x16x32_bf16 v[50:53], v[50:53], v[114:117], v[62:65]
	s_nop 0
	v_mul_f32_e32 v66, v72, v73
	v_cvt_pk_bf16_f32 v71, v71, v66
	global_store_dwordx2 v[100:101], v[70:71], off
	v_mfma_f32_16x16x32_bf16 v[38:41], v[38:41], v[110:113], v[106:109]
	s_nop 0
	v_mov_b64_e32 v[62:63], v[188:189]
	v_mov_b64_e32 v[64:65], v[190:191]
	v_lshlrev_b32_e32 v66, 16, v118
	v_and_b32_e32 v67, 0xffff0000, v118
	v_mfma_f32_16x16x32_bf16 v[54:57], v[54:57], v[134:137], 0
	v_mfma_f32_16x16x32_bf16 v[20:23], v[20:23], v[110:113], v[90:93]
	s_nop 0
	v_mul_f32_e32 v38, v38, v62
	v_mul_f32_e32 v39, v39, v63
	v_mul_f32_e32 v38, v38, v66
	v_mul_f32_e32 v40, v40, v64
	v_mul_f32_e32 v39, v39, v67
	v_cvt_pk_bf16_f32 v62, v38, v39
	v_lshlrev_b32_e32 v38, 16, v119
	v_mul_f32_e32 v63, v40, v38
	v_mul_f32_e32 v64, v41, v65
	v_mfma_f32_16x16x32_bf16 v[38:41], v[46:49], v[130:133], v[54:57]
	v_and_b32_e32 v65, 0xffff0000, v119
	v_mul_f32_e32 v46, v64, v65
	v_cvt_pk_bf16_f32 v63, v63, v46
	global_store_dwordx2 v[98:99], v[62:63], off offset:32
	v_mfma_f32_16x16x32_bf16 v[38:41], v[42:45], v[114:117], v[38:41]
	v_mov_b64_e32 v[42:43], v[192:193]
	v_mov_b64_e32 v[44:45], v[194:195]
	v_lshlrev_b32_e32 v46, 16, v120
	v_and_b32_e32 v47, 0xffff0000, v120
	v_lshlrev_b32_e32 v48, 16, v121
	v_and_b32_e32 v49, 0xffff0000, v121
	v_mfma_f32_16x16x32_bf16 v[16:19], v[16:19], v[110:113], v[74:77]
	v_mul_f32_e32 v20, v20, v42
	v_mul_f32_e32 v21, v21, v43
	v_mul_f32_e32 v22, v22, v44
	v_mul_f32_e32 v23, v23, v45
	v_mul_f32_e32 v20, v20, v46
	v_mul_f32_e32 v21, v21, v47
	v_mul_f32_e32 v22, v22, v48
	v_mul_f32_e32 v23, v23, v49
	v_cvt_pk_bf16_f32 v20, v20, v21
	v_cvt_pk_bf16_f32 v21, v22, v23
	global_store_dwordx2 v[98:99], v[20:21], off offset:64
	v_mov_b64_e32 v[20:21], v[196:197]
	v_mov_b64_e32 v[22:23], v[198:199]
	v_lshlrev_b32_e32 v42, 16, v122
	v_and_b32_e32 v43, 0xffff0000, v122
	v_lshlrev_b32_e32 v44, 16, v123
	v_and_b32_e32 v45, 0xffff0000, v123
	v_mfma_f32_16x16x32_bf16 v[8:11], v[8:11], v[134:137], 0
	v_mul_f32_e32 v16, v16, v20
	v_mul_f32_e32 v17, v17, v21
	v_mul_f32_e32 v18, v18, v22
	v_mul_f32_e32 v19, v19, v23
	v_mul_f32_e32 v16, v16, v42
	v_mul_f32_e32 v17, v17, v43
	v_mul_f32_e32 v18, v18, v44
	v_mul_f32_e32 v19, v19, v45
	v_cvt_pk_bf16_f32 v16, v16, v17
	v_cvt_pk_bf16_f32 v17, v18, v19
	global_store_dwordx2 v[98:99], v[16:17], off offset:96
	v_mov_b64_e32 v[16:17], v[200:201]
	v_mov_b64_e32 v[18:19], v[202:203]
	v_mfma_f32_16x16x32_bf16 v[20:23], v[34:37], v[110:113], v[58:61]
	v_lshlrev_b32_e32 v34, 16, v124
	v_and_b32_e32 v35, 0xffff0000, v124
	v_lshlrev_b32_e32 v36, 16, v125
	v_and_b32_e32 v37, 0xffff0000, v125
	v_mfma_f32_16x16x32_bf16 v[4:7], v[4:7], v[130:133], v[8:11]
	s_nop 1
	v_mul_f32_e32 v16, v20, v16
	v_mul_f32_e32 v17, v21, v17
	v_mul_f32_e32 v18, v22, v18
	v_mul_f32_e32 v19, v23, v19
	v_mul_f32_e32 v16, v16, v34
	v_mul_f32_e32 v17, v17, v35
	v_mul_f32_e32 v18, v18, v36
	v_mul_f32_e32 v19, v19, v37
	v_cvt_pk_bf16_f32 v16, v16, v17
	v_cvt_pk_bf16_f32 v17, v18, v19
	global_store_dwordx2 v[98:99], v[16:17], off offset:128
	v_mov_b64_e32 v[16:17], v[210:211]
	v_mov_b64_e32 v[18:19], v[212:213]
	v_mfma_f32_16x16x32_bf16 v[20:23], v[28:31], v[110:113], v[50:53]
	v_lshlrev_b32_e32 v28, 16, v126
	v_and_b32_e32 v29, 0xffff0000, v126
	v_lshlrev_b32_e32 v30, 16, v127
	v_and_b32_e32 v31, 0xffff0000, v127
	v_mfma_f32_16x16x32_bf16 v[0:3], v[0:3], v[114:117], v[4:7]
	s_nop 1
	v_mul_f32_e32 v16, v20, v16
	v_mul_f32_e32 v17, v21, v17
	v_mul_f32_e32 v18, v22, v18
	v_mul_f32_e32 v19, v23, v19
	v_mul_f32_e32 v16, v16, v28
	v_mul_f32_e32 v17, v17, v29
	v_mul_f32_e32 v18, v18, v30
	v_mul_f32_e32 v19, v19, v31
	v_cvt_pk_bf16_f32 v16, v16, v17
	v_cvt_pk_bf16_f32 v17, v18, v19
	global_store_dwordx2 v[98:99], v[16:17], off offset:160
	v_mov_b64_e32 v[16:17], v[214:215]
	v_mov_b64_e32 v[18:19], v[216:217]
	v_mfma_f32_16x16x32_bf16 v[20:23], v[24:27], v[110:113], v[38:41]
	v_lshlrev_b32_e32 v24, 16, v128
	v_and_b32_e32 v25, 0xffff0000, v128
	v_lshlrev_b32_e32 v26, 16, v129
	v_and_b32_e32 v27, 0xffff0000, v129
	v_mfma_f32_16x16x32_bf16 v[0:3], v[12:15], v[110:113], v[0:3]
	v_lshlrev_b32_e32 v4, 16, v82
	v_and_b32_e32 v5, 0xffff0000, v82
	v_lshlrev_b32_e32 v6, 16, v83
	v_and_b32_e32 v7, 0xffff0000, v83
	v_mul_f32_e32 v16, v20, v16
	v_mul_f32_e32 v17, v21, v17
	v_mul_f32_e32 v18, v22, v18
	v_mul_f32_e32 v19, v23, v19
	v_mul_f32_e32 v16, v16, v24
	v_mul_f32_e32 v17, v17, v25
	v_mul_f32_e32 v18, v18, v26
	v_mul_f32_e32 v19, v19, v27
	v_cvt_pk_bf16_f32 v16, v16, v17
	v_cvt_pk_bf16_f32 v17, v18, v19
	global_store_dwordx2 v[98:99], v[16:17], off offset:192
	v_mov_b64_e32 v[16:17], v[228:229]
	v_mov_b64_e32 v[18:19], v[230:231]
	v_xor_b32_e32 v20, 16, v226
	v_xor_b32_e32 v21, 32, v226
	v_cmp_lt_i32_e32 vcc, v20, v162
	v_readlane_b32 s10, v251, 33
	v_readlane_b32 s11, v251, 34
	v_cndmask_b32_e32 v20, v226, v20, vcc
	v_cmp_lt_i32_e32 vcc, v21, v162
	s_add_u32 s66, s10, s8
	v_lshlrev_b32_e32 v100, 2, v20
	v_cndmask_b32_e32 v8, v226, v21, vcc
	v_lshlrev_b32_e32 v101, 2, v8
	s_addc_u32 s67, s11, 0
	v_mul_f32_e32 v0, v0, v16
	v_mul_f32_e32 v1, v1, v17
	v_mul_f32_e32 v2, v2, v18
	v_mul_f32_e32 v3, v3, v19
	v_mul_f32_e32 v0, v0, v4
	v_mul_f32_e32 v1, v1, v5
	v_mul_f32_e32 v2, v2, v6
	v_mul_f32_e32 v3, v3, v7
	v_cvt_pk_bf16_f32 v0, v0, v1
	v_cvt_pk_bf16_f32 v1, v2, v3
	global_store_dwordx2 v[98:99], v[0:1], off offset:224
	s_barrier
	s_mov_b32 s48, 0
	s_branch .Lpf_issue
